# prep conversion loop + ret_intra V and cross/gate loads widened to dwordx4 with permlane32_swap
# speedup vs baseline: 1.0164x; 1.0130x over previous
.LBB0_450:
	s_andn2_saveexec_b64 s[4:5], s[70:71]
	v_cvt_f32_u32_e32 v20, v38
	v_mul_f32_e32 v20, v23, v20
	v_exp_f32_e32 v37, v20
	s_or_b64 exec, exec, s[4:5]
	v_mul_f32_e32 v8, v8, v28
	v_mul_f32_e32 v9, v9, v29
	v_mul_f32_e32 v6, v6, v26
	v_mul_f32_e32 v7, v7, v27
	v_mul_f32_e32 v4, v4, v24
	v_mul_f32_e32 v5, v5, v25
	v_mul_f32_e32 v2, v2, v19
	v_mul_f32_e32 v3, v3, v22
	v_mul_f32_e32 v16, v16, v36
	v_mul_f32_e32 v14, v14, v34
	v_mul_f32_e32 v15, v15, v35
	v_mul_f32_e32 v12, v12, v32
	v_mul_f32_e32 v13, v13, v33
	v_mul_f32_e32 v10, v10, v30
	v_mul_f32_e32 v11, v11, v31
	v_mul_f32_e32 v17, v17, v37
	v_cvt_pk_bf16_f32 v2, v2, v3
	v_cvt_pk_bf16_f32 v3, v4, v5
	v_cvt_pk_bf16_f32 v4, v6, v7
	v_cvt_pk_bf16_f32 v5, v8, v9
	v_or_b32_e32 v75, v0, v190
	s_barrier
	v_cvt_pk_bf16_f32 v6, v10, v11
	v_cvt_pk_bf16_f32 v7, v12, v13
	v_cvt_pk_bf16_f32 v8, v14, v15
	v_cvt_pk_bf16_f32 v9, v16, v17
	ds_write_b128 v191, v[2:5]
	ds_write_b128 v191, v[6:9] offset:1024
	v_or_b32_e32 v2, v75, v71
	v_lshlrev_b32_e32 v34, 14, v2
	v_mov_b32_e32 v35, v1
	v_ashrrev_i32_e32 v19, 31, v18
	v_lshl_add_u64 v[2:3], s[62:63], 0, v[34:35]
	v_lshlrev_b64 v[36:37], 1, v[18:19]
	v_lshl_add_u64 v[2:3], v[2:3], 0, v[36:37]
	v_lshl_add_u64 v[36:37], v[68:69], 0, v[36:37]
	v_lshl_add_u64 v[156:157], v[36:37], 0, v[34:35]
	v_bfe_u32 v36, v189, 5, 1
	v_lshlrev_b32_e32 v36, 3, v36
	v_mov_b32_e32 v37, 0
	v_lshl_add_u64 v[156:157], v[156:157], 0, v[36:37]
	s_mov_b32 s4, 0x80000
	v_mov_b32_e32 v77, v1
	v_add_co_u32_e64 v38, s[4:5], s4, v156
	v_lshl_add_u64 v[32:33], v[2:3], 0, v[76:77]
	v_lshl_add_u64 v[32:33], v[32:33], 0, v[36:37]
	s_nop 0
	v_addc_co_u32_e64 v39, s[4:5], 0, v157, s[4:5]
	s_waitcnt lgkmcnt(0)
	s_barrier
	global_load_dwordx4 v[2:5], v[32:33], off
	global_load_dwordx4 v[6:9], v[32:33], off offset:32
	global_load_dwordx4 v[10:13], v[32:33], off offset:64
	global_load_dwordx4 v[14:17], v[32:33], off offset:96
	global_load_dwordx4 v[18:21], v[32:33], off offset:128
	global_load_dwordx4 v[22:25], v[32:33], off offset:160
	global_load_dwordx4 v[26:29], v[32:33], off offset:192
	global_load_dwordx4 v[30:33], v[32:33], off offset:224
	global_load_dwordx4 v[34:37], v[38:39], off
	global_load_dwordx4 v[80:83], v[38:39], off offset:32
	global_load_dwordx4 v[84:87], v[38:39], off offset:64
	global_load_dwordx4 v[88:91], v[38:39], off offset:96
	global_load_dwordx4 v[92:95], v[38:39], off offset:128
	global_load_dwordx4 v[96:99], v[38:39], off offset:160
	global_load_dwordx4 v[100:103], v[38:39], off offset:192
	global_load_dwordx4 v[104:107], v[38:39], off offset:224
	ds_read_b128 v[108:111], v181
	ds_read_b128 v[112:115], v181 offset:1024
	ds_read_b128 v[116:119], v181 offset:2048
	ds_read_b128 v[120:123], v181 offset:3072
	ds_read_b128 v[124:127], v181 offset:4096
	ds_read_b128 v[128:131], v181 offset:5120
	ds_read_b128 v[132:135], v181 offset:6144
	ds_read_b128 v[136:139], v181 offset:7168
	s_waitcnt vmcnt(15)
	v_permlane32_swap_b32_e32 v2, v4
	v_permlane32_swap_b32_e32 v3, v5
	s_waitcnt vmcnt(14)
	v_permlane32_swap_b32_e32 v6, v8
	v_permlane32_swap_b32_e32 v7, v9
	s_waitcnt lgkmcnt(7)
	v_mfma_f32_32x32x16_bf16 v[50:65], v[2:5], v[108:111], 0
	s_waitcnt vmcnt(13)
	v_permlane32_swap_b32_e32 v10, v12
	v_permlane32_swap_b32_e32 v11, v13
	s_waitcnt lgkmcnt(6)
	v_mfma_f32_32x32x16_bf16 v[50:65], v[6:9], v[112:115], v[50:65]
	s_waitcnt vmcnt(12)
	v_permlane32_swap_b32_e32 v14, v16
	v_permlane32_swap_b32_e32 v15, v17
	s_waitcnt lgkmcnt(5)
	v_mfma_f32_32x32x16_bf16 v[50:65], v[10:13], v[116:119], v[50:65]
	s_waitcnt vmcnt(11)
	v_permlane32_swap_b32_e32 v18, v20
	v_permlane32_swap_b32_e32 v19, v21
	s_waitcnt lgkmcnt(4)
	v_mfma_f32_32x32x16_bf16 v[50:65], v[14:17], v[120:123], v[50:65]
	s_waitcnt vmcnt(10)
	v_permlane32_swap_b32_e32 v22, v24
	v_permlane32_swap_b32_e32 v23, v25
	s_waitcnt lgkmcnt(3)
	v_mfma_f32_32x32x16_bf16 v[50:65], v[18:21], v[124:127], v[50:65]
	s_waitcnt vmcnt(9)
	v_permlane32_swap_b32_e32 v26, v28
	v_permlane32_swap_b32_e32 v27, v29
	s_waitcnt lgkmcnt(2)
	v_mfma_f32_32x32x16_bf16 v[50:65], v[22:25], v[128:131], v[50:65]
	s_waitcnt vmcnt(8)
	v_permlane32_swap_b32_e32 v30, v32
	v_permlane32_swap_b32_e32 v31, v33
	s_waitcnt lgkmcnt(1)
	v_mfma_f32_32x32x16_bf16 v[50:65], v[26:29], v[132:135], v[50:65]
	s_nop 1
	s_waitcnt lgkmcnt(0)
	v_mfma_f32_32x32x16_bf16 v[50:65], v[30:33], v[136:139], v[50:65]
	s_mov_b32 s4, 0x100000
	v_add_co_u32_e64 v18, s[4:5], s4, v156
	s_nop 1
	v_addc_co_u32_e64 v19, s[4:5], 0, v157, s[4:5]
	global_load_dwordx4 v[2:5], v[18:19], off
	global_load_dwordx4 v[6:9], v[18:19], off offset:32
	global_load_dwordx4 v[10:13], v[18:19], off offset:64
	global_load_dwordx4 v[14:17], v[18:19], off offset:96
	global_load_dwordx4 v[140:143], v[18:19], off offset:128
	global_load_dwordx4 v[144:147], v[18:19], off offset:160
	global_load_dwordx4 v[148:151], v[18:19], off offset:192
	global_load_dwordx4 v[152:155], v[18:19], off offset:224
	s_waitcnt vmcnt(15)
	v_permlane32_swap_b32_e32 v34, v36
	v_permlane32_swap_b32_e32 v35, v37
	s_waitcnt vmcnt(14)
	v_permlane32_swap_b32_e32 v80, v82
	v_permlane32_swap_b32_e32 v81, v83
	s_waitcnt lgkmcnt(7)
	v_mfma_f32_32x32x16_bf16 v[34:49], v[34:37], v[108:111], 0
	s_waitcnt vmcnt(13)
	v_permlane32_swap_b32_e32 v84, v86
	v_permlane32_swap_b32_e32 v85, v87
	s_waitcnt lgkmcnt(6)
	v_mfma_f32_32x32x16_bf16 v[34:49], v[80:83], v[112:115], v[34:49]
	s_waitcnt vmcnt(12)
	v_permlane32_swap_b32_e32 v88, v90
	v_permlane32_swap_b32_e32 v89, v91
	s_waitcnt lgkmcnt(5)
	v_mfma_f32_32x32x16_bf16 v[34:49], v[84:87], v[116:119], v[34:49]
	s_waitcnt vmcnt(11)
	v_permlane32_swap_b32_e32 v92, v94
	v_permlane32_swap_b32_e32 v93, v95
	s_waitcnt lgkmcnt(4)
	v_mfma_f32_32x32x16_bf16 v[34:49], v[88:91], v[120:123], v[34:49]
	s_waitcnt vmcnt(10)
	v_permlane32_swap_b32_e32 v96, v98
	v_permlane32_swap_b32_e32 v97, v99
	s_waitcnt lgkmcnt(3)
	v_mfma_f32_32x32x16_bf16 v[34:49], v[92:95], v[124:127], v[34:49]
	s_waitcnt vmcnt(9)
	v_permlane32_swap_b32_e32 v100, v102
	v_permlane32_swap_b32_e32 v101, v103
	s_waitcnt lgkmcnt(2)
	v_mfma_f32_32x32x16_bf16 v[34:49], v[96:99], v[128:131], v[34:49]
	s_waitcnt vmcnt(8)
	v_permlane32_swap_b32_e32 v104, v106
	v_permlane32_swap_b32_e32 v105, v107
	s_waitcnt lgkmcnt(1)
	v_mfma_f32_32x32x16_bf16 v[34:49], v[100:103], v[132:135], v[34:49]
	s_nop 1
	s_waitcnt lgkmcnt(0)
	v_mfma_f32_32x32x16_bf16 v[34:49], v[104:107], v[136:139], v[34:49]
	s_mov_b32 s4, 0x180000
	v_add_co_u32_e64 v18, s[4:5], s4, v156
	s_nop 1
	v_addc_co_u32_e64 v19, s[4:5], 0, v157, s[4:5]
	global_load_dwordx4 v[80:83], v[18:19], off
	global_load_dwordx4 v[84:87], v[18:19], off offset:32
	global_load_dwordx4 v[88:91], v[18:19], off offset:64
	global_load_dwordx4 v[92:95], v[18:19], off offset:96
	global_load_dwordx4 v[96:99], v[18:19], off offset:128
	global_load_dwordx4 v[100:103], v[18:19], off offset:160
	global_load_dwordx4 v[104:107], v[18:19], off offset:192
	global_load_dwordx4 v[156:159], v[18:19], off offset:224
	s_waitcnt vmcnt(15)
	v_permlane32_swap_b32_e32 v2, v4
	v_permlane32_swap_b32_e32 v3, v5
	s_waitcnt vmcnt(14)
	v_permlane32_swap_b32_e32 v6, v8
	v_permlane32_swap_b32_e32 v7, v9
	s_waitcnt lgkmcnt(7)
	v_mfma_f32_32x32x16_bf16 v[18:33], v[2:5], v[108:111], 0
	s_waitcnt vmcnt(13)
	v_permlane32_swap_b32_e32 v10, v12
	v_permlane32_swap_b32_e32 v11, v13
	s_waitcnt lgkmcnt(6)
	v_mfma_f32_32x32x16_bf16 v[18:33], v[6:9], v[112:115], v[18:33]
	s_waitcnt vmcnt(12)
	v_permlane32_swap_b32_e32 v14, v16
	v_permlane32_swap_b32_e32 v15, v17
	s_waitcnt lgkmcnt(5)
	v_mfma_f32_32x32x16_bf16 v[18:33], v[10:13], v[116:119], v[18:33]
	s_waitcnt vmcnt(11)
	v_permlane32_swap_b32_e32 v140, v142
	v_permlane32_swap_b32_e32 v141, v143
	s_waitcnt lgkmcnt(4)
	v_mfma_f32_32x32x16_bf16 v[18:33], v[14:17], v[120:123], v[18:33]
	s_waitcnt vmcnt(10)
	v_permlane32_swap_b32_e32 v144, v146
	v_permlane32_swap_b32_e32 v145, v147
	s_waitcnt lgkmcnt(3)
	v_mfma_f32_32x32x16_bf16 v[18:33], v[140:143], v[124:127], v[18:33]
	s_waitcnt vmcnt(9)
	v_permlane32_swap_b32_e32 v148, v150
	v_permlane32_swap_b32_e32 v149, v151
	s_waitcnt lgkmcnt(2)
	v_mfma_f32_32x32x16_bf16 v[18:33], v[144:147], v[128:131], v[18:33]
	s_waitcnt vmcnt(8)
	v_permlane32_swap_b32_e32 v152, v154
	v_permlane32_swap_b32_e32 v153, v155
	s_waitcnt lgkmcnt(1)
	v_mfma_f32_32x32x16_bf16 v[18:33], v[148:151], v[132:135], v[18:33]
	s_waitcnt vmcnt(7)
	v_permlane32_swap_b32_e32 v80, v82
	v_permlane32_swap_b32_e32 v81, v83
	s_waitcnt lgkmcnt(0)
	v_mfma_f32_32x32x16_bf16 v[18:33], v[152:155], v[136:139], v[18:33]
	s_waitcnt vmcnt(6)
	v_permlane32_swap_b32_e32 v84, v86
	v_permlane32_swap_b32_e32 v85, v87
	s_waitcnt lgkmcnt(7)
	v_mfma_f32_32x32x16_bf16 v[2:17], v[80:83], v[108:111], 0
	s_waitcnt vmcnt(5)
	v_permlane32_swap_b32_e32 v88, v90
	v_permlane32_swap_b32_e32 v89, v91
	s_waitcnt lgkmcnt(6)
	v_mfma_f32_32x32x16_bf16 v[2:17], v[84:87], v[112:115], v[2:17]
	s_waitcnt vmcnt(4)
	v_permlane32_swap_b32_e32 v92, v94
	v_permlane32_swap_b32_e32 v93, v95
	s_waitcnt lgkmcnt(5)
	v_mfma_f32_32x32x16_bf16 v[2:17], v[88:91], v[116:119], v[2:17]
	s_waitcnt vmcnt(3)
	v_permlane32_swap_b32_e32 v96, v98
	v_permlane32_swap_b32_e32 v97, v99
	s_waitcnt lgkmcnt(4)
	v_mfma_f32_32x32x16_bf16 v[2:17], v[92:95], v[120:123], v[2:17]
	s_waitcnt vmcnt(2)
	v_permlane32_swap_b32_e32 v100, v102
	v_permlane32_swap_b32_e32 v101, v103
	s_waitcnt lgkmcnt(3)
	v_mfma_f32_32x32x16_bf16 v[2:17], v[96:99], v[124:127], v[2:17]
	s_waitcnt vmcnt(1)
	v_permlane32_swap_b32_e32 v104, v106
	v_permlane32_swap_b32_e32 v105, v107
	s_waitcnt lgkmcnt(2)
	v_mfma_f32_32x32x16_bf16 v[2:17], v[100:103], v[128:131], v[2:17]
	s_waitcnt vmcnt(0)
	v_permlane32_swap_b32_e32 v156, v158
	v_permlane32_swap_b32_e32 v157, v159
	s_waitcnt lgkmcnt(1)
	v_mfma_f32_32x32x16_bf16 v[2:17], v[104:107], v[132:135], v[2:17]
	s_nop 1
	s_waitcnt lgkmcnt(0)
	v_mfma_f32_32x32x16_bf16 v[2:17], v[156:159], v[136:139], v[2:17]
	v_or_b32_e32 v0, v70, v0
	v_or_b32_e32 v80, v0, v78
	v_mov_b32_e32 v81, v79
	v_lshlrev_b64 v[80:81], 1, v[80:81]
	v_bfe_u32 v112, v189, 5, 1
	v_lshlrev_b32_e32 v112, 3, v112
	v_mov_b32_e32 v113, 0
	v_lshl_add_u64 v[80:81], v[80:81], 0, v[112:113]
	v_lshl_add_u64 v[82:83], s[64:65], 0, v[80:81]
	v_lshl_add_u64 v[84:85], s[66:67], 0, v[80:81]
	v_lshl_add_u64 v[80:81], s[68:69], 0, v[80:81]
	global_load_dwordx4 v[114:117], v[82:83], off
	global_load_dwordx4 v[122:125], v[82:83], off offset:32
	global_load_dwordx4 v[130:133], v[82:83], off offset:64
	global_load_dwordx4 v[138:141], v[82:83], off offset:96
	global_load_dwordx4 v[146:149], v[82:83], off offset:128
	global_load_dwordx4 v[154:157], v[82:83], off offset:160
	global_load_dwordx4 v[162:165], v[82:83], off offset:192
	global_load_dwordx4 v[170:173], v[82:83], off offset:224
	global_load_dwordx4 v[118:121], v[84:85], off
	global_load_dwordx4 v[126:129], v[84:85], off offset:32
	global_load_dwordx4 v[134:137], v[84:85], off offset:64
	global_load_dwordx4 v[142:145], v[84:85], off offset:96
	global_load_dwordx4 v[150:153], v[84:85], off offset:128
	global_load_dwordx4 v[158:161], v[84:85], off offset:160
	global_load_dwordx4 v[166:169], v[84:85], off offset:192
	global_load_dwordx4 v[174:177], v[84:85], off offset:224
	global_load_dwordx4 v[108:111], v[80:81], off
	global_load_dwordx4 v[104:107], v[80:81], off offset:32
	global_load_dwordx4 v[100:103], v[80:81], off offset:64
	global_load_dwordx4 v[96:99], v[80:81], off offset:96
	global_load_dwordx4 v[92:95], v[80:81], off offset:128
	global_load_dwordx4 v[88:91], v[80:81], off offset:160
	global_load_dwordx4 v[84:87], v[80:81], off offset:192
	global_load_dwordx4 v[80:83], v[80:81], off offset:224
	s_waitcnt vmcnt(0)
	v_permlane32_swap_b32_e32 v114, v116
	v_permlane32_swap_b32_e32 v115, v117
	v_permlane32_swap_b32_e32 v122, v124
	v_permlane32_swap_b32_e32 v123, v125
	v_permlane32_swap_b32_e32 v130, v132
	v_permlane32_swap_b32_e32 v131, v133
	v_permlane32_swap_b32_e32 v138, v140
	v_permlane32_swap_b32_e32 v139, v141
	v_permlane32_swap_b32_e32 v146, v148
	v_permlane32_swap_b32_e32 v147, v149
	v_permlane32_swap_b32_e32 v154, v156
	v_permlane32_swap_b32_e32 v155, v157
	v_permlane32_swap_b32_e32 v162, v164
	v_permlane32_swap_b32_e32 v163, v165
	v_permlane32_swap_b32_e32 v170, v172
	v_permlane32_swap_b32_e32 v171, v173
	v_permlane32_swap_b32_e32 v118, v120
	v_permlane32_swap_b32_e32 v119, v121
	v_permlane32_swap_b32_e32 v126, v128
	v_permlane32_swap_b32_e32 v127, v129
	v_permlane32_swap_b32_e32 v134, v136
	v_permlane32_swap_b32_e32 v135, v137
	v_permlane32_swap_b32_e32 v142, v144
	v_permlane32_swap_b32_e32 v143, v145
	v_permlane32_swap_b32_e32 v150, v152
	v_permlane32_swap_b32_e32 v151, v153
	v_permlane32_swap_b32_e32 v158, v160
	v_permlane32_swap_b32_e32 v159, v161
	v_permlane32_swap_b32_e32 v166, v168
	v_permlane32_swap_b32_e32 v167, v169
	v_permlane32_swap_b32_e32 v174, v176
	v_permlane32_swap_b32_e32 v175, v177
	v_permlane32_swap_b32_e32 v108, v110
	v_permlane32_swap_b32_e32 v109, v111
	v_permlane32_swap_b32_e32 v104, v106
	v_permlane32_swap_b32_e32 v105, v107
	v_permlane32_swap_b32_e32 v100, v102
	v_permlane32_swap_b32_e32 v101, v103
	v_permlane32_swap_b32_e32 v96, v98
	v_permlane32_swap_b32_e32 v97, v99
	v_permlane32_swap_b32_e32 v92, v94
	v_permlane32_swap_b32_e32 v93, v95
	v_permlane32_swap_b32_e32 v88, v90
	v_permlane32_swap_b32_e32 v89, v91
	v_permlane32_swap_b32_e32 v84, v86
	v_permlane32_swap_b32_e32 v85, v87
	v_permlane32_swap_b32_e32 v80, v82
	v_permlane32_swap_b32_e32 v81, v83
	v_swap_b32 v116, v118
	v_swap_b32 v117, v119
	v_swap_b32 v124, v126
	v_swap_b32 v125, v127
	v_swap_b32 v132, v134
	v_swap_b32 v133, v135
	v_swap_b32 v140, v142
	v_swap_b32 v141, v143
	v_swap_b32 v148, v150
	v_swap_b32 v149, v151
	v_swap_b32 v156, v158
	v_swap_b32 v157, v159
	v_swap_b32 v168, v170
	v_swap_b32 v169, v171
	v_swap_b32 v108, v110
	v_swap_b32 v109, v111
	v_swap_b32 v104, v106
	v_swap_b32 v105, v107
	v_swap_b32 v100, v102
	v_swap_b32 v101, v103
	v_swap_b32 v96, v98
	v_swap_b32 v97, v99
	v_swap_b32 v92, v94
	v_swap_b32 v93, v95
	v_swap_b32 v88, v90
	v_swap_b32 v89, v91
	v_swap_b32 v84, v86
	v_swap_b32 v85, v87
	v_swap_b32 v80, v82
	v_swap_b32 v81, v83
	v_lshlrev_b32_e32 v112, 16, v114
	v_and_b32_e32 v113, 0xffff0000, v114
	s_waitcnt vmcnt(43)
	v_lshlrev_b32_e32 v178, 16, v116
	v_and_b32_e32 v179, 0xffff0000, v116
	v_pk_add_f32 v[112:113], v[112:113], v[178:179]
	v_lshlrev_b32_e32 v114, 16, v117
	v_pk_add_f32 v[112:113], v[50:51], v[112:113]
	v_lshlrev_b32_e32 v50, 16, v115
	v_and_b32_e32 v51, 0xffff0000, v115
	v_and_b32_e32 v115, 0xffff0000, v117
	v_pk_add_f32 v[50:51], v[50:51], v[114:115]
	v_add_f32_e32 v0, 0, v112
	v_pk_add_f32 v[114:115], v[52:53], v[50:51]
	v_add_f32_e32 v52, v113, v0
	v_mul_f32_e32 v0, v113, v113
	v_pk_fma_f32 v[50:51], v[112:113], v[112:113], v[0:1] op_sel_hi:[1,1,0]
	v_add_f32_e32 v0, v114, v52
	v_lshlrev_b32_e32 v52, 16, v118
	v_and_b32_e32 v53, 0xffff0000, v118
	s_waitcnt vmcnt(42)
	v_lshlrev_b32_e32 v116, 16, v120
	v_and_b32_e32 v117, 0xffff0000, v120
	v_pk_add_f32 v[52:53], v[52:53], v[116:117]
	v_pk_fma_f32 v[50:51], v[114:115], v[114:115], v[50:51]
	v_add_f32_e32 v77, v115, v0
	v_mul_f32_e32 v0, v115, v115
	v_pk_add_f32 v[116:117], v[54:55], v[52:53]
	v_lshlrev_b32_e32 v52, 16, v119
	v_and_b32_e32 v53, 0xffff0000, v119
	v_lshlrev_b32_e32 v54, 16, v121
	v_and_b32_e32 v55, 0xffff0000, v121
	v_pk_add_f32 v[50:51], v[0:1], v[50:51] op_sel_hi:[0,1]
	v_pk_add_f32 v[52:53], v[52:53], v[54:55]
	v_add_f32_e32 v0, v116, v77
	v_pk_add_f32 v[118:119], v[56:57], v[52:53]
	v_pk_fma_f32 v[50:51], v[116:117], v[116:117], v[50:51]
	v_add_f32_e32 v52, v117, v0
	v_mul_f32_e32 v0, v117, v117
	v_pk_add_f32 v[50:51], v[0:1], v[50:51] op_sel_hi:[0,1]
	v_add_f32_e32 v0, v118, v52
	v_lshlrev_b32_e32 v52, 16, v122
	v_and_b32_e32 v53, 0xffff0000, v122
	s_waitcnt vmcnt(41)
	v_lshlrev_b32_e32 v54, 16, v124
	v_and_b32_e32 v55, 0xffff0000, v124
	v_pk_add_f32 v[52:53], v[52:53], v[54:55]
	v_pk_fma_f32 v[50:51], v[118:119], v[118:119], v[50:51]
	v_add_f32_e32 v56, v119, v0
	v_mul_f32_e32 v0, v119, v119
	v_pk_add_f32 v[120:121], v[58:59], v[52:53]
	v_lshlrev_b32_e32 v52, 16, v123
	v_and_b32_e32 v53, 0xffff0000, v123
	v_lshlrev_b32_e32 v54, 16, v125
	v_and_b32_e32 v55, 0xffff0000, v125
	v_pk_add_f32 v[50:51], v[0:1], v[50:51] op_sel_hi:[0,1]
	v_pk_add_f32 v[52:53], v[52:53], v[54:55]
	v_add_f32_e32 v0, v120, v56
	v_pk_add_f32 v[122:123], v[60:61], v[52:53]
	v_pk_fma_f32 v[50:51], v[120:121], v[120:121], v[50:51]
	v_add_f32_e32 v52, v121, v0
	v_mul_f32_e32 v0, v121, v121
	v_pk_add_f32 v[50:51], v[0:1], v[50:51] op_sel_hi:[0,1]
	v_add_f32_e32 v0, v122, v52
	v_lshlrev_b32_e32 v52, 16, v126
	v_and_b32_e32 v53, 0xffff0000, v126
	s_waitcnt vmcnt(40)
	v_lshlrev_b32_e32 v54, 16, v128
	v_and_b32_e32 v55, 0xffff0000, v128
	v_pk_add_f32 v[52:53], v[52:53], v[54:55]
	v_pk_fma_f32 v[50:51], v[122:123], v[122:123], v[50:51]
	v_add_f32_e32 v56, v123, v0
	v_mul_f32_e32 v0, v123, v123
	v_pk_add_f32 v[124:125], v[62:63], v[52:53]
	v_lshlrev_b32_e32 v52, 16, v127
	v_and_b32_e32 v53, 0xffff0000, v127
	v_lshlrev_b32_e32 v54, 16, v129
	v_and_b32_e32 v55, 0xffff0000, v129
	v_pk_add_f32 v[50:51], v[0:1], v[50:51] op_sel_hi:[0,1]
	v_pk_add_f32 v[52:53], v[52:53], v[54:55]
	v_add_f32_e32 v0, v124, v56
	v_pk_add_f32 v[126:127], v[64:65], v[52:53]
	v_pk_fma_f32 v[50:51], v[124:125], v[124:125], v[50:51]
	v_add_f32_e32 v52, v125, v0
	v_mul_f32_e32 v0, v125, v125
	v_pk_add_f32 v[50:51], v[0:1], v[50:51] op_sel_hi:[0,1]
	v_add_f32_e32 v0, v126, v52
	s_waitcnt vmcnt(35)
	v_lshlrev_b32_e32 v52, 16, v130
	v_and_b32_e32 v53, 0xffff0000, v130
	s_waitcnt vmcnt(31)
	v_lshlrev_b32_e32 v54, 16, v132
	v_and_b32_e32 v55, 0xffff0000, v132
	v_pk_add_f32 v[52:53], v[52:53], v[54:55]
	v_pk_fma_f32 v[50:51], v[126:127], v[126:127], v[50:51]
	v_add_f32_e32 v56, v127, v0
	v_mul_f32_e32 v0, v127, v127
	v_pk_add_f32 v[128:129], v[34:35], v[52:53]
	v_lshlrev_b32_e32 v34, 16, v131
	v_and_b32_e32 v35, 0xffff0000, v131
	v_lshlrev_b32_e32 v52, 16, v133
	v_and_b32_e32 v53, 0xffff0000, v133
	v_pk_add_f32 v[50:51], v[0:1], v[50:51] op_sel_hi:[0,1]
	v_pk_add_f32 v[34:35], v[34:35], v[52:53]
	v_add_f32_e32 v0, v128, v56
	v_pk_add_f32 v[130:131], v[36:37], v[34:35]
	v_pk_fma_f32 v[34:35], v[128:129], v[128:129], v[50:51]
	v_add_f32_e32 v36, v129, v0
	v_mul_f32_e32 v0, v129, v129
	v_pk_add_f32 v[34:35], v[0:1], v[34:35] op_sel_hi:[0,1]
	v_add_f32_e32 v0, v130, v36
	v_lshlrev_b32_e32 v36, 16, v134
	v_and_b32_e32 v37, 0xffff0000, v134
	s_waitcnt vmcnt(30)
	v_lshlrev_b32_e32 v50, 16, v136
	v_and_b32_e32 v51, 0xffff0000, v136
	v_pk_add_f32 v[36:37], v[36:37], v[50:51]
	v_pk_fma_f32 v[34:35], v[130:131], v[130:131], v[34:35]
	v_add_f32_e32 v52, v131, v0
	v_mul_f32_e32 v0, v131, v131
	v_pk_add_f32 v[132:133], v[38:39], v[36:37]
	v_lshlrev_b32_e32 v36, 16, v135
	v_and_b32_e32 v37, 0xffff0000, v135
	v_lshlrev_b32_e32 v38, 16, v137
	v_and_b32_e32 v39, 0xffff0000, v137
	v_pk_add_f32 v[34:35], v[0:1], v[34:35] op_sel_hi:[0,1]
	v_pk_add_f32 v[36:37], v[36:37], v[38:39]
	v_add_f32_e32 v0, v132, v52
	v_pk_add_f32 v[134:135], v[40:41], v[36:37]
	v_pk_fma_f32 v[34:35], v[132:133], v[132:133], v[34:35]
	v_add_f32_e32 v36, v133, v0
	v_mul_f32_e32 v0, v133, v133
	v_pk_add_f32 v[34:35], v[0:1], v[34:35] op_sel_hi:[0,1]
	v_add_f32_e32 v0, v134, v36
	v_lshlrev_b32_e32 v36, 16, v138
	v_and_b32_e32 v37, 0xffff0000, v138
	s_waitcnt vmcnt(29)
	v_lshlrev_b32_e32 v38, 16, v140
	v_and_b32_e32 v39, 0xffff0000, v140
	v_pk_add_f32 v[36:37], v[36:37], v[38:39]
	v_pk_fma_f32 v[34:35], v[134:135], v[134:135], v[34:35]
	v_add_f32_e32 v40, v135, v0
	v_mul_f32_e32 v0, v135, v135
	v_pk_add_f32 v[136:137], v[42:43], v[36:37]
	v_lshlrev_b32_e32 v36, 16, v139
	v_and_b32_e32 v37, 0xffff0000, v139
	v_lshlrev_b32_e32 v38, 16, v141
	v_and_b32_e32 v39, 0xffff0000, v141
	v_pk_add_f32 v[34:35], v[0:1], v[34:35] op_sel_hi:[0,1]
	v_pk_add_f32 v[36:37], v[36:37], v[38:39]
	v_add_f32_e32 v0, v136, v40
	v_pk_add_f32 v[138:139], v[44:45], v[36:37]
	v_pk_fma_f32 v[34:35], v[136:137], v[136:137], v[34:35]
	v_add_f32_e32 v36, v137, v0
	v_mul_f32_e32 v0, v137, v137
	v_pk_add_f32 v[34:35], v[0:1], v[34:35] op_sel_hi:[0,1]
	v_add_f32_e32 v0, v138, v36
	v_lshlrev_b32_e32 v36, 16, v142
	v_and_b32_e32 v37, 0xffff0000, v142
	s_waitcnt vmcnt(28)
	v_lshlrev_b32_e32 v38, 16, v144
	v_and_b32_e32 v39, 0xffff0000, v144
	v_pk_add_f32 v[36:37], v[36:37], v[38:39]
	v_pk_fma_f32 v[34:35], v[138:139], v[138:139], v[34:35]
	v_add_f32_e32 v40, v139, v0
	v_mul_f32_e32 v0, v139, v139
	v_pk_add_f32 v[140:141], v[46:47], v[36:37]
	v_lshlrev_b32_e32 v36, 16, v143
	v_and_b32_e32 v37, 0xffff0000, v143
	v_lshlrev_b32_e32 v38, 16, v145
	v_and_b32_e32 v39, 0xffff0000, v145
	v_pk_add_f32 v[34:35], v[0:1], v[34:35] op_sel_hi:[0,1]
	v_pk_add_f32 v[36:37], v[36:37], v[38:39]
	v_add_f32_e32 v0, v140, v40
	v_pk_add_f32 v[142:143], v[48:49], v[36:37]
	v_pk_fma_f32 v[34:35], v[140:141], v[140:141], v[34:35]
	v_add_f32_e32 v36, v141, v0
	v_mul_f32_e32 v0, v141, v141
	v_pk_add_f32 v[34:35], v[0:1], v[34:35] op_sel_hi:[0,1]
	v_add_f32_e32 v0, v142, v36
	s_waitcnt vmcnt(23)
	v_lshlrev_b32_e32 v36, 16, v146
	v_and_b32_e32 v37, 0xffff0000, v146
	s_waitcnt vmcnt(19)
	v_lshlrev_b32_e32 v38, 16, v148
	v_and_b32_e32 v39, 0xffff0000, v148
	v_pk_add_f32 v[36:37], v[36:37], v[38:39]
	v_pk_fma_f32 v[34:35], v[142:143], v[142:143], v[34:35]
	v_add_f32_e32 v40, v143, v0
	v_mul_f32_e32 v0, v143, v143
	v_pk_add_f32 v[144:145], v[18:19], v[36:37]
	v_lshlrev_b32_e32 v18, 16, v147
	v_and_b32_e32 v19, 0xffff0000, v147
	v_lshlrev_b32_e32 v36, 16, v149
	v_and_b32_e32 v37, 0xffff0000, v149
	v_pk_add_f32 v[34:35], v[0:1], v[34:35] op_sel_hi:[0,1]
	v_pk_add_f32 v[18:19], v[18:19], v[36:37]
	v_add_f32_e32 v0, v144, v40
	v_pk_add_f32 v[146:147], v[20:21], v[18:19]
	v_pk_fma_f32 v[18:19], v[144:145], v[144:145], v[34:35]
	v_add_f32_e32 v20, v145, v0
	v_mul_f32_e32 v0, v145, v145
	v_pk_add_f32 v[18:19], v[0:1], v[18:19] op_sel_hi:[0,1]
	v_add_f32_e32 v0, v146, v20
	v_lshlrev_b32_e32 v20, 16, v150
	v_and_b32_e32 v21, 0xffff0000, v150
	s_waitcnt vmcnt(18)
	v_lshlrev_b32_e32 v34, 16, v152
	v_and_b32_e32 v35, 0xffff0000, v152
	v_pk_add_f32 v[20:21], v[20:21], v[34:35]
	v_pk_fma_f32 v[18:19], v[146:147], v[146:147], v[18:19]
	v_add_f32_e32 v36, v147, v0
	v_mul_f32_e32 v0, v147, v147
	v_pk_add_f32 v[148:149], v[22:23], v[20:21]
	v_lshlrev_b32_e32 v20, 16, v151
	v_and_b32_e32 v21, 0xffff0000, v151
	v_lshlrev_b32_e32 v22, 16, v153
	v_and_b32_e32 v23, 0xffff0000, v153
	v_pk_add_f32 v[18:19], v[0:1], v[18:19] op_sel_hi:[0,1]
	v_pk_add_f32 v[20:21], v[20:21], v[22:23]
	v_add_f32_e32 v0, v148, v36
	v_pk_add_f32 v[150:151], v[24:25], v[20:21]
	v_pk_fma_f32 v[18:19], v[148:149], v[148:149], v[18:19]
	v_add_f32_e32 v20, v149, v0
	v_mul_f32_e32 v0, v149, v149
	v_pk_add_f32 v[18:19], v[0:1], v[18:19] op_sel_hi:[0,1]
	v_add_f32_e32 v0, v150, v20
	v_lshlrev_b32_e32 v20, 16, v154
	v_and_b32_e32 v21, 0xffff0000, v154
	s_waitcnt vmcnt(17)
	v_lshlrev_b32_e32 v22, 16, v156
	v_and_b32_e32 v23, 0xffff0000, v156
	v_pk_add_f32 v[20:21], v[20:21], v[22:23]
	v_pk_fma_f32 v[18:19], v[150:151], v[150:151], v[18:19]
	v_add_f32_e32 v24, v151, v0
	v_mul_f32_e32 v0, v151, v151
	v_pk_add_f32 v[152:153], v[26:27], v[20:21]
	v_lshlrev_b32_e32 v20, 16, v155
	v_and_b32_e32 v21, 0xffff0000, v155
	v_lshlrev_b32_e32 v22, 16, v157
	v_and_b32_e32 v23, 0xffff0000, v157
	v_pk_add_f32 v[18:19], v[0:1], v[18:19] op_sel_hi:[0,1]
	v_pk_add_f32 v[20:21], v[20:21], v[22:23]
	v_add_f32_e32 v0, v152, v24
	v_pk_add_f32 v[154:155], v[28:29], v[20:21]
	v_pk_fma_f32 v[18:19], v[152:153], v[152:153], v[18:19]
	v_add_f32_e32 v20, v153, v0
	v_mul_f32_e32 v0, v153, v153
	v_pk_add_f32 v[18:19], v[0:1], v[18:19] op_sel_hi:[0,1]
	v_add_f32_e32 v0, v154, v20
	v_lshlrev_b32_e32 v20, 16, v158
	v_and_b32_e32 v21, 0xffff0000, v158
	s_waitcnt vmcnt(16)
	v_lshlrev_b32_e32 v22, 16, v160
	v_and_b32_e32 v23, 0xffff0000, v160
	v_pk_add_f32 v[20:21], v[20:21], v[22:23]
	v_pk_fma_f32 v[18:19], v[154:155], v[154:155], v[18:19]
	v_add_f32_e32 v24, v155, v0
	v_mul_f32_e32 v0, v155, v155
	v_pk_add_f32 v[156:157], v[30:31], v[20:21]
	v_lshlrev_b32_e32 v20, 16, v159
	v_and_b32_e32 v21, 0xffff0000, v159
	v_lshlrev_b32_e32 v22, 16, v161
	v_and_b32_e32 v23, 0xffff0000, v161
	v_pk_add_f32 v[18:19], v[0:1], v[18:19] op_sel_hi:[0,1]
	v_pk_add_f32 v[20:21], v[20:21], v[22:23]
	v_add_f32_e32 v0, v156, v24
	v_pk_add_f32 v[158:159], v[32:33], v[20:21]
	v_pk_fma_f32 v[18:19], v[156:157], v[156:157], v[18:19]
	v_add_f32_e32 v20, v157, v0
	v_mul_f32_e32 v0, v157, v157
	v_pk_add_f32 v[18:19], v[0:1], v[18:19] op_sel_hi:[0,1]
	v_add_f32_e32 v0, v158, v20
	s_waitcnt vmcnt(11)
	v_lshlrev_b32_e32 v20, 16, v162
	v_and_b32_e32 v21, 0xffff0000, v162
	s_waitcnt vmcnt(7)
	v_lshlrev_b32_e32 v22, 16, v166
	v_and_b32_e32 v23, 0xffff0000, v166
	v_pk_add_f32 v[20:21], v[20:21], v[22:23]
	v_pk_fma_f32 v[18:19], v[158:159], v[158:159], v[18:19]
	v_add_f32_e32 v24, v159, v0
	v_mul_f32_e32 v0, v159, v159
	v_pk_add_f32 v[160:161], v[2:3], v[20:21]
	v_lshlrev_b32_e32 v2, 16, v163
	v_and_b32_e32 v3, 0xffff0000, v163
	v_lshlrev_b32_e32 v20, 16, v167
	v_and_b32_e32 v21, 0xffff0000, v167
	v_pk_add_f32 v[18:19], v[0:1], v[18:19] op_sel_hi:[0,1]
	v_pk_add_f32 v[2:3], v[2:3], v[20:21]
	v_add_f32_e32 v0, v160, v24
	v_pk_add_f32 v[162:163], v[4:5], v[2:3]
	v_pk_fma_f32 v[2:3], v[160:161], v[160:161], v[18:19]
	v_add_f32_e32 v4, v161, v0
	v_mul_f32_e32 v0, v161, v161
	v_pk_add_f32 v[2:3], v[0:1], v[2:3] op_sel_hi:[0,1]
	v_add_f32_e32 v0, v162, v4
	v_lshlrev_b32_e32 v4, 16, v164
	v_and_b32_e32 v5, 0xffff0000, v164
	s_waitcnt vmcnt(6)
	v_lshlrev_b32_e32 v18, 16, v170
	v_and_b32_e32 v19, 0xffff0000, v170
	v_pk_add_f32 v[4:5], v[4:5], v[18:19]
	v_add_f32_e32 v0, v163, v0
	v_pk_add_f32 v[166:167], v[6:7], v[4:5]
	v_lshlrev_b32_e32 v4, 16, v165
	v_and_b32_e32 v5, 0xffff0000, v165
	v_lshlrev_b32_e32 v6, 16, v171
	v_and_b32_e32 v7, 0xffff0000, v171
	v_pk_fma_f32 v[2:3], v[162:163], v[162:163], v[2:3]
	v_pk_add_f32 v[4:5], v[4:5], v[6:7]
	v_add_f32_e32 v6, v166, v0
	v_mul_f32_e32 v0, v163, v163
	v_pk_add_f32 v[164:165], v[8:9], v[4:5]
	v_mov_b32_e32 v4, v166
	v_mov_b32_e32 v5, v163
	v_pk_add_f32 v[2:3], v[0:1], v[2:3] op_sel_hi:[0,1]
	v_add_f32_e32 v0, v167, v6
	v_pk_fma_f32 v[2:3], v[4:5], v[4:5], v[2:3]
	v_add_f32_e32 v6, v164, v0
	v_mul_f32_e32 v0, v167, v167
	v_mov_b32_e32 v4, v164
	v_mov_b32_e32 v5, v167
	v_pk_add_f32 v[2:3], v[0:1], v[2:3] op_sel_hi:[0,1]
	v_pk_fma_f32 v[2:3], v[4:5], v[4:5], v[2:3]
	v_add_f32_e32 v0, v165, v6
	v_lshlrev_b32_e32 v4, 16, v168
	v_and_b32_e32 v5, 0xffff0000, v168
	s_waitcnt vmcnt(5)
	v_lshlrev_b32_e32 v6, 16, v174
	v_and_b32_e32 v7, 0xffff0000, v174
	v_pk_add_f32 v[4:5], v[4:5], v[6:7]
	v_lshlrev_b32_e32 v6, 16, v175
	v_pk_add_f32 v[170:171], v[10:11], v[4:5]
	v_lshlrev_b32_e32 v4, 16, v169
	v_and_b32_e32 v5, 0xffff0000, v169
	v_and_b32_e32 v7, 0xffff0000, v175
	v_pk_add_f32 v[4:5], v[4:5], v[6:7]
	v_add_f32_e32 v6, v170, v0
	v_mul_f32_e32 v0, v165, v165
	v_pk_add_f32 v[168:169], v[12:13], v[4:5]
	v_mov_b32_e32 v4, v170
	v_mov_b32_e32 v5, v165
	v_pk_add_f32 v[2:3], v[0:1], v[2:3] op_sel_hi:[0,1]
	v_add_f32_e32 v0, v171, v6
	v_pk_fma_f32 v[2:3], v[4:5], v[4:5], v[2:3]
	v_add_f32_e32 v6, v168, v0
	v_mul_f32_e32 v0, v171, v171
	v_mov_b32_e32 v4, v168
	v_mov_b32_e32 v5, v171
	v_pk_add_f32 v[2:3], v[0:1], v[2:3] op_sel_hi:[0,1]
	v_pk_fma_f32 v[2:3], v[4:5], v[4:5], v[2:3]
	v_add_f32_e32 v77, v169, v6
	v_lshlrev_b32_e32 v4, 16, v172
	v_and_b32_e32 v5, 0xffff0000, v172
	s_waitcnt vmcnt(4)
	v_lshlrev_b32_e32 v6, 16, v176
	v_and_b32_e32 v7, 0xffff0000, v176
	v_pk_add_f32 v[4:5], v[4:5], v[6:7]
	v_lshlrev_b32_e32 v6, 16, v177
	v_pk_add_f32 v[174:175], v[14:15], v[4:5]
	v_lshlrev_b32_e32 v4, 16, v173
	v_and_b32_e32 v5, 0xffff0000, v173
	v_and_b32_e32 v7, 0xffff0000, v177
	v_pk_add_f32 v[4:5], v[4:5], v[6:7]
	v_mul_f32_e32 v0, v169, v169
	v_pk_add_f32 v[172:173], v[16:17], v[4:5]
	v_mov_b32_e32 v4, v174
	v_mov_b32_e32 v5, v169
	v_pk_add_f32 v[2:3], v[0:1], v[2:3] op_sel_hi:[0,1]
	v_pk_fma_f32 v[2:3], v[4:5], v[4:5], v[2:3]
	v_mul_f32_e32 v0, v175, v175
	v_mov_b32_e32 v4, v172
	v_mov_b32_e32 v5, v175
	v_pk_add_f32 v[2:3], v[0:1], v[2:3] op_sel_hi:[0,1]
	v_lshlrev_b32_e32 v0, 11, v226
	v_pk_fma_f32 v[178:179], v[4:5], v[4:5], v[2:3]
	v_lshl_add_u64 v[2:3], v[72:73], 0, v[0:1]
	global_load_dwordx4 v[62:65], v[2:3], off
	global_load_dwordx4 v[58:61], v[2:3], off offset:32
	global_load_dwordx4 v[54:57], v[2:3], off offset:64
	global_load_dwordx4 v[50:53], v[2:3], off offset:96
	global_load_dwordx4 v[46:49], v[2:3], off offset:128
	global_load_dwordx4 v[42:45], v[2:3], off offset:160
	global_load_dwordx4 v[38:41], v[2:3], off offset:192
	global_load_dwordx4 v[34:37], v[2:3], off offset:224
	global_load_dwordx4 v[30:33], v[2:3], off offset:256
	global_load_dwordx4 v[26:29], v[2:3], off offset:288
	global_load_dwordx4 v[22:25], v[2:3], off offset:320
	global_load_dwordx4 v[18:21], v[2:3], off offset:352
	global_load_dwordx4 v[14:17], v[2:3], off offset:384
	global_load_dwordx4 v[10:13], v[2:3], off offset:416
	global_load_dwordx4 v[6:9], v[2:3], off offset:448
	s_nop 0
	global_load_dwordx4 v[2:5], v[2:3], off offset:480
	v_add_f32_e32 v0, v174, v77
	v_pk_mul_f32 v[176:177], v[172:173], v[172:173]
	v_add_f32_e32 v0, v175, v0
	v_add_f32_e32 v176, v172, v0
	v_pk_mov_b32 v[178:179], v[172:173], v[178:179] op_sel:[1,0]
	s_nop 0
	v_pk_add_f32 v[176:177], v[178:179], v[176:177]
	ds_bpermute_b32 v178, v192, v176
	ds_bpermute_b32 v179, v192, v177
	s_and_saveexec_b64 s[4:5], vcc
	s_cbranch_execz .LBB0_387
	s_waitcnt lgkmcnt(0)
	v_pk_add_f32 v[176:177], v[176:177], v[178:179]
	ds_write_b64 v193, v[176:177] offset:8192
	s_branch .LBB0_387
